# P2|P3 barrier: late-tile workgroups (no P2 dependence) arrive without waiting; MISC[10] computed at the P3|P4 barrier
# baseline (speedup 1.0000x reference)
; #define LAS __attribute__((address_space(3)))
; __device__ __forceinline__ unsigned long long rt() { return __builtin_amdgcn_s_memrealtime(); }
; __global__ void __launch_bounds__(NWAVES * 64, 2) fwd(Args args) {
;     ...
;     if (IN(2)) {
;         const unsigned long long amp_t0_2 = (PROBE_AMP == 2 || PROBE_AMP == 21) ? rt() : 0ull;
;         {
;             { const int h_ = (int)blockIdx.x & 3; LAS float* cw = (LAS float*)(lds + CONVW_OFF);
;               for (int i = tid; i < 1536; i += NWAVES * 64) { const int part = i >> 9, j = (i >> 7) & 3, cc = i & 127; cw[i] = args.in[3][j * 1536 + part * 512 + h_ * 128 + cc]; } }
;             DnRaw R; dn_load_raw(R, (int)blockIdx.x, DNR, HALO, GBT, tid);
;             { HgRaw H; hg_load_raw(H, HGR + (size_t)blockIdx.x * 32768, tid);
;               for (int u = (int)blockIdx.x; u < 1024; u += G) p2_hg_unit(lds, HGR + (size_t)u * 32768, OLH + (size_t)u * 8192, DEC + (size_t)u * 128, tid, lane, wave, H, (u + G < 1024) ? HGR + (size_t)(u + G) * 32768 : nullptr); }
.LBB0_312:
.LBB0_317:
	s_cmp_lt_i32 s56, 3
	s_cselect_b64 s[6:7], -1, 0
	s_cmp_gt_i32 s57, 2
	s_cselect_b64 s[8:9], -1, 0
	s_and_b64 s[6:7], s[6:7], s[8:9]
	s_andn2_b64 vcc, exec, s[6:7]
	s_cbranch_vccnz .LBB0_660
	v_writelane_b32 v240, s2, 40
	v_writelane_b32 v240, s34, 41
	v_writelane_b32 v240, s68, 42
	v_writelane_b32 v240, s69, 43
	s_and_b32 s3, s2, 7
	s_lshl_b32 s3, s3, 3
	s_bfe_u32 s4, s2, 0x30003
	s_or_b32 s3, s3, s4
	s_lshl_b32 s3, s3, 4
	s_lshr_b32 s4, s2, 6
	s_or_b32 s2, s3, s4
	s_or_b32 s98, s2, 15
	s_mov_b32 s34, 4
	s_lshl_b32 s3, s2, 7
	v_lshrrev_b32_e32 v2, 7, v0
	s_and_b32 s3, s3, 0x180
	v_and_b32_e32 v1, 0x7f, v0
	v_mul_u32_u24_e32 v2, 0x600, v2
	v_or3_b32 v1, v2, s3, v1
	s_mov_b32 s3, 0
	v_add_u32_e32 v4, 0x21000, v184
	s_mov_b64 s[6:7], 0
	v_mov_b32_e32 v3, 0
	s_movk_i32 s4, 0x3ff

;     __host__ __device__ void init(int M_, int G_, int c_) { so.init(M_, 1024, G_, c_); }
;     __host__ __device__ void init(int M_, int G_, int c_) { so.init(M_, 3072, G_, c_); }
;     __host__ __device__ void init(int M_, int start_, int stride_, int limit_) { so.init(M_, 3072, stride_, start_); start = start_; stride = stride_; limit = limit_; }
; #define BOTH(k) (IN(k) && (k) + 1 < hi)
; #define GRID_BAR() xcd_barrier(bar)
; __global__ void __launch_bounds__(NWAVES * 64, 2) fwd(Args args) {
;     ...
;         if (BOTH(2)) GRID_BAR();
;     ...
;         if (blockIdx.x < 32) p3_dn_scan(lds, ((int)blockIdx.x & 7) * 4 + ((int)blockIdx.x >> 3), DNR, DEC + 1024 * 128, BNB, lane, wave);
;         else {
;             if (blockIdx.x < 64) { p3_hg_scan((int)blockIdx.x - 32, HGR, DEC, tid); __syncthreads(); }
;             pg8::Gemm g{XB, WING_T, M, 3072, D, D, D}; pg8::LateOrder S;
;             S.init(M, (int)blockIdx.x - 64, G - 64, 768);
;             pg8::EpiInProj E{HGR, DNR, HALO, GAB, lbl};
;             if (blockIdx.x >= 64) pg8::gemm_phase<pg8::EpiInProj, pg8::LateOrder, true, true>(lds + RING_OFF, g, S, E);
.Lxb3_chk:
	s_cmpk_gt_u32 s2, 63
	s_cbranch_scc1 .LBB0_659

; __global__ void __launch_bounds__(NWAVES * 64, 2) fwd(Args args) {
;     ...
;         if (tid == 0) MISC[10] = (whole && __hip_atomic_load((unsigned*)(ctl + CW_NONLOCAL), RLX_AGENT) == 0u) ? 1u : 0u;
.Lxb4_done:
	s_waitcnt vmcnt(0)
	v_readlane_b32 s8, v240, 42
	v_readlane_b32 s9, v240, 43
	v_mov_b32_e32 v1, 0
	s_nop 1
	s_andn2_b64 vcc, exec, s[8:9]
	s_cbranch_vccnz .Lts1_m10
	v_mov_b32_e32 v1, 0x28000
	global_load_dword v1, v1, s[60:61] offset:2048 sc1
	s_waitcnt vmcnt(0)
	v_cmp_eq_u32_e32 vcc, 0, v1
	s_nop 1
	v_cndmask_b32_e64 v1, 0, 1, vcc
.Lts1_m10:
	v_mov_b32_e32 v2, 0x22968
	ds_write_b32 v2, v1
.LBB0_889:
	s_or_b64 exec, exec, s[0:1]
	s_waitcnt lgkmcnt(0)
	s_barrier
